# speedup vs baseline: 1.0038x; 1.0038x over previous
.LBB0_962:
	v_lshl_add_u32 v146, s35, 8, v142
	v_lshl_or_b32 v140, s34, 8, v144
	v_ashrrev_i32_e32 v147, 31, v146
	v_ashrrev_i32_e32 v141, 31, v140
	v_lshlrev_b64 v[148:149], 14, v[146:147]
	v_lshl_add_u64 v[148:149], s[48:49], 0, v[148:149]
	v_lshlrev_b64 v[150:151], 1, v[140:141]
	v_max_f32_e32 v122, 0, v122
	v_max_f32_e32 v123, 0, v123
	v_lshl_add_u64 v[140:141], v[148:149], 0, v[150:151]
	v_pk_mul_f32 v[148:149], v[122:123], v[122:123]
	v_max_f32_e32 v124, 0, v124
	v_max_f32_e32 v126, 0, v126
	v_max_f32_e32 v127, 0, v127
	v_max_f32_e32 v122, 0, v128
	v_max_f32_e32 v123, 0, v129
	v_max_f32_e32 v125, 0, v125
	v_pk_mul_f32 v[126:127], v[126:127], v[126:127]
	v_pk_mul_f32 v[128:129], v[122:123], v[122:123]
	v_pk_mul_f32 v[152:153], v[124:125], v[124:125]
	v_cvt_pk_bf16_f32 v122, v126, v127
	v_cvt_pk_bf16_f32 v123, v128, v129
	v_cvt_pk_bf16_f32 v124, v148, v149
	v_cvt_pk_bf16_f32 v125, v152, v153
	v_max_f32_e32 v114, 0, v114
	v_max_f32_e32 v115, 0, v115
	global_store_dwordx4 v[140:141], v[122:125], off
	s_nop 1
	v_pk_mul_f32 v[122:123], v[114:115], v[114:115]
	v_max_f32_e32 v116, 0, v116
	v_max_f32_e32 v118, 0, v118
	v_max_f32_e32 v119, 0, v119
	v_max_f32_e32 v114, 0, v120
	v_max_f32_e32 v115, 0, v121
	v_max_f32_e32 v117, 0, v117
	v_pk_mul_f32 v[118:119], v[118:119], v[118:119]
	v_pk_mul_f32 v[120:121], v[114:115], v[114:115]
	v_pk_mul_f32 v[124:125], v[116:117], v[116:117]
	v_cvt_pk_bf16_f32 v114, v118, v119
	v_cvt_pk_bf16_f32 v115, v120, v121
	v_cvt_pk_bf16_f32 v116, v122, v123
	v_cvt_pk_bf16_f32 v117, v124, v125
	v_max_f32_e32 v106, 0, v106
	v_max_f32_e32 v107, 0, v107
	global_store_dwordx4 v[140:141], v[114:117], off offset:256
	s_nop 1
	v_or_b32_e32 v114, 16, v146
	v_pk_mul_f32 v[116:117], v[106:107], v[106:107]
	v_ashrrev_i32_e32 v115, 31, v114
	v_max_f32_e32 v108, 0, v108
	v_lshlrev_b64 v[114:115], 14, v[114:115]
	v_max_f32_e32 v110, 0, v110
	v_max_f32_e32 v111, 0, v111
	v_max_f32_e32 v106, 0, v112
	v_max_f32_e32 v107, 0, v113
	v_max_f32_e32 v109, 0, v109
	v_lshl_add_u64 v[114:115], s[48:49], 0, v[114:115]
	v_pk_mul_f32 v[110:111], v[110:111], v[110:111]
	v_pk_mul_f32 v[112:113], v[106:107], v[106:107]
	v_pk_mul_f32 v[118:119], v[108:109], v[108:109]
	v_lshl_add_u64 v[114:115], v[114:115], 0, v[150:151]
	v_cvt_pk_bf16_f32 v106, v110, v111
	v_cvt_pk_bf16_f32 v107, v112, v113
	v_cvt_pk_bf16_f32 v108, v116, v117
	v_cvt_pk_bf16_f32 v109, v118, v119
	v_max_f32_e32 v98, 0, v98
	v_max_f32_e32 v99, 0, v99
	global_store_dwordx4 v[114:115], v[106:109], off
	s_nop 1
	v_pk_mul_f32 v[106:107], v[98:99], v[98:99]
	v_max_f32_e32 v100, 0, v100
	v_max_f32_e32 v102, 0, v102
	v_max_f32_e32 v103, 0, v103
	v_max_f32_e32 v98, 0, v104
	v_max_f32_e32 v99, 0, v105
	v_max_f32_e32 v101, 0, v101
	v_pk_mul_f32 v[102:103], v[102:103], v[102:103]
	v_pk_mul_f32 v[104:105], v[98:99], v[98:99]
	v_pk_mul_f32 v[108:109], v[100:101], v[100:101]
	v_cvt_pk_bf16_f32 v98, v102, v103
	v_cvt_pk_bf16_f32 v99, v104, v105
	v_cvt_pk_bf16_f32 v100, v106, v107
	v_cvt_pk_bf16_f32 v101, v108, v109
	v_max_f32_e32 v90, 0, v90
	v_max_f32_e32 v91, 0, v91
	global_store_dwordx4 v[114:115], v[98:101], off offset:256
	s_nop 1
	v_or_b32_e32 v98, 32, v146
	v_pk_mul_f32 v[100:101], v[90:91], v[90:91]
	v_ashrrev_i32_e32 v99, 31, v98
	v_max_f32_e32 v92, 0, v92
	v_lshlrev_b64 v[98:99], 14, v[98:99]
	v_max_f32_e32 v94, 0, v94
	v_max_f32_e32 v95, 0, v95
	v_max_f32_e32 v90, 0, v96
	v_max_f32_e32 v91, 0, v97
	v_max_f32_e32 v93, 0, v93
	v_lshl_add_u64 v[98:99], s[48:49], 0, v[98:99]
	v_pk_mul_f32 v[94:95], v[94:95], v[94:95]
	v_pk_mul_f32 v[96:97], v[90:91], v[90:91]
	v_pk_mul_f32 v[102:103], v[92:93], v[92:93]
	v_lshl_add_u64 v[98:99], v[98:99], 0, v[150:151]
	v_cvt_pk_bf16_f32 v90, v94, v95
	v_cvt_pk_bf16_f32 v91, v96, v97
	v_cvt_pk_bf16_f32 v92, v100, v101
	v_cvt_pk_bf16_f32 v93, v102, v103
	v_max_f32_e32 v82, 0, v82
	v_max_f32_e32 v83, 0, v83
	global_store_dwordx4 v[98:99], v[90:93], off
	s_nop 1
	v_pk_mul_f32 v[90:91], v[82:83], v[82:83]
	v_max_f32_e32 v84, 0, v84
	v_max_f32_e32 v86, 0, v86
	v_max_f32_e32 v87, 0, v87
	v_max_f32_e32 v82, 0, v88
	v_max_f32_e32 v83, 0, v89
	v_max_f32_e32 v85, 0, v85
	v_pk_mul_f32 v[86:87], v[86:87], v[86:87]
	v_pk_mul_f32 v[88:89], v[82:83], v[82:83]
	v_pk_mul_f32 v[92:93], v[84:85], v[84:85]
	v_cvt_pk_bf16_f32 v82, v86, v87
	v_cvt_pk_bf16_f32 v83, v88, v89
	v_cvt_pk_bf16_f32 v84, v90, v91
	v_cvt_pk_bf16_f32 v85, v92, v93
	v_max_f32_e32 v74, 0, v74
	v_max_f32_e32 v75, 0, v75
	global_store_dwordx4 v[98:99], v[82:85], off offset:256
	s_nop 1
	v_or_b32_e32 v82, 48, v146
	v_pk_mul_f32 v[84:85], v[74:75], v[74:75]
	v_ashrrev_i32_e32 v83, 31, v82
	v_max_f32_e32 v76, 0, v76
	v_lshlrev_b64 v[82:83], 14, v[82:83]
	v_max_f32_e32 v78, 0, v78
	v_max_f32_e32 v79, 0, v79
	v_max_f32_e32 v74, 0, v80
	v_max_f32_e32 v75, 0, v81
	v_max_f32_e32 v77, 0, v77
	v_lshl_add_u64 v[82:83], s[48:49], 0, v[82:83]
	v_pk_mul_f32 v[78:79], v[78:79], v[78:79]
	v_pk_mul_f32 v[80:81], v[74:75], v[74:75]
	v_pk_mul_f32 v[86:87], v[76:77], v[76:77]
	v_lshl_add_u64 v[82:83], v[82:83], 0, v[150:151]
	v_cvt_pk_bf16_f32 v74, v78, v79
	v_cvt_pk_bf16_f32 v75, v80, v81
	v_cvt_pk_bf16_f32 v76, v84, v85
	v_cvt_pk_bf16_f32 v77, v86, v87
	v_max_f32_e32 v66, 0, v66
	v_max_f32_e32 v67, 0, v67
	global_store_dwordx4 v[82:83], v[74:77], off
	s_nop 1
	v_pk_mul_f32 v[74:75], v[66:67], v[66:67]
	v_max_f32_e32 v68, 0, v68
	v_max_f32_e32 v70, 0, v70
	v_max_f32_e32 v71, 0, v71
	v_max_f32_e32 v66, 0, v72
	v_max_f32_e32 v67, 0, v73
	v_max_f32_e32 v69, 0, v69
	v_pk_mul_f32 v[70:71], v[70:71], v[70:71]
	v_pk_mul_f32 v[72:73], v[66:67], v[66:67]
	v_pk_mul_f32 v[76:77], v[68:69], v[68:69]
	v_cvt_pk_bf16_f32 v66, v70, v71
	v_cvt_pk_bf16_f32 v67, v72, v73
	v_cvt_pk_bf16_f32 v68, v74, v75
	v_cvt_pk_bf16_f32 v69, v76, v77
	v_max_f32_e32 v58, 0, v58
	v_max_f32_e32 v59, 0, v59
	global_store_dwordx4 v[82:83], v[66:69], off offset:256
	s_nop 1
	v_pk_mul_f32 v[68:69], v[58:59], v[58:59]
	v_max_f32_e32 v62, 0, v62
	v_max_f32_e32 v63, 0, v63
	v_max_f32_e32 v60, 0, v60
	v_pk_mul_f32 v[62:63], v[62:63], v[62:63]
	v_max_f32_e32 v58, 0, v64
	v_max_f32_e32 v59, 0, v65
	v_max_f32_e32 v61, 0, v61
	s_mov_b32 s3, 0x200000
	v_pk_mul_f32 v[64:65], v[58:59], v[58:59]
	v_pk_mul_f32 v[70:71], v[60:61], v[60:61]
	v_cvt_pk_bf16_f32 v58, v62, v63
	v_add_co_u32_e32 v62, vcc, s3, v140
	v_cvt_pk_bf16_f32 v59, v64, v65
	v_cvt_pk_bf16_f32 v60, v68, v69
	v_cvt_pk_bf16_f32 v61, v70, v71
	v_addc_co_u32_e32 v63, vcc, 0, v141, vcc
	v_max_f32_e32 v50, 0, v50
	v_max_f32_e32 v51, 0, v51
	global_store_dwordx4 v[62:63], v[58:61], off
	s_nop 1
	v_pk_mul_f32 v[58:59], v[50:51], v[50:51]
	v_max_f32_e32 v52, 0, v52
	v_max_f32_e32 v54, 0, v54
	v_max_f32_e32 v55, 0, v55
	v_max_f32_e32 v50, 0, v56
	v_max_f32_e32 v51, 0, v57
	v_max_f32_e32 v53, 0, v53
	s_mov_b64 s[16:17], 0x200000
	v_pk_mul_f32 v[54:55], v[54:55], v[54:55]
	v_pk_mul_f32 v[56:57], v[50:51], v[50:51]
	v_pk_mul_f32 v[60:61], v[52:53], v[52:53]
	v_lshl_add_u64 v[66:67], v[140:141], 0, s[16:17]
	v_cvt_pk_bf16_f32 v50, v54, v55
	v_cvt_pk_bf16_f32 v51, v56, v57
	v_cvt_pk_bf16_f32 v52, v58, v59
	v_cvt_pk_bf16_f32 v53, v60, v61
	v_max_f32_e32 v42, 0, v42
	v_max_f32_e32 v43, 0, v43
	global_store_dwordx4 v[66:67], v[50:53], off offset:256
	s_nop 1
	v_pk_mul_f32 v[52:53], v[42:43], v[42:43]
	v_max_f32_e32 v46, 0, v46
	v_max_f32_e32 v47, 0, v47
	v_max_f32_e32 v44, 0, v44
	v_pk_mul_f32 v[46:47], v[46:47], v[46:47]
	v_max_f32_e32 v42, 0, v48
	v_max_f32_e32 v43, 0, v49
	v_max_f32_e32 v45, 0, v45
	s_mov_b32 s3, 0x240000
	v_pk_mul_f32 v[48:49], v[42:43], v[42:43]
	v_pk_mul_f32 v[54:55], v[44:45], v[44:45]
	v_cvt_pk_bf16_f32 v42, v46, v47
	v_add_co_u32_e32 v46, vcc, s3, v140
	v_cvt_pk_bf16_f32 v43, v48, v49
	v_cvt_pk_bf16_f32 v44, v52, v53
	v_cvt_pk_bf16_f32 v45, v54, v55
	v_addc_co_u32_e32 v47, vcc, 0, v141, vcc
	v_max_f32_e32 v34, 0, v34
	v_max_f32_e32 v35, 0, v35
	global_store_dwordx4 v[46:47], v[42:45], off
	s_nop 1
	v_pk_mul_f32 v[42:43], v[34:35], v[34:35]
	v_max_f32_e32 v36, 0, v36
	v_max_f32_e32 v38, 0, v38
	v_max_f32_e32 v39, 0, v39
	v_max_f32_e32 v34, 0, v40
	v_max_f32_e32 v35, 0, v41
	v_max_f32_e32 v37, 0, v37
	s_mov_b64 s[16:17], 0x240000
	v_pk_mul_f32 v[38:39], v[38:39], v[38:39]
	v_pk_mul_f32 v[40:41], v[34:35], v[34:35]
	v_pk_mul_f32 v[44:45], v[36:37], v[36:37]
	v_lshl_add_u64 v[50:51], v[140:141], 0, s[16:17]
	v_cvt_pk_bf16_f32 v34, v38, v39
	v_cvt_pk_bf16_f32 v35, v40, v41
	v_cvt_pk_bf16_f32 v36, v42, v43
	v_cvt_pk_bf16_f32 v37, v44, v45
	v_max_f32_e32 v26, 0, v26
	v_max_f32_e32 v27, 0, v27
	global_store_dwordx4 v[50:51], v[34:37], off offset:256
	s_nop 1
	v_pk_mul_f32 v[36:37], v[26:27], v[26:27]
	v_max_f32_e32 v30, 0, v30
	v_max_f32_e32 v31, 0, v31
	v_max_f32_e32 v28, 0, v28
	v_pk_mul_f32 v[30:31], v[30:31], v[30:31]
	v_max_f32_e32 v26, 0, v32
	v_max_f32_e32 v27, 0, v33
	v_max_f32_e32 v29, 0, v29
	s_mov_b32 s3, 0x280000
	v_pk_mul_f32 v[32:33], v[26:27], v[26:27]
	v_pk_mul_f32 v[38:39], v[28:29], v[28:29]
	v_cvt_pk_bf16_f32 v26, v30, v31
	v_add_co_u32_e32 v30, vcc, s3, v140
	v_cvt_pk_bf16_f32 v27, v32, v33
	v_cvt_pk_bf16_f32 v28, v36, v37
	v_cvt_pk_bf16_f32 v29, v38, v39
	v_addc_co_u32_e32 v31, vcc, 0, v141, vcc
	v_max_f32_e32 v18, 0, v18
	v_max_f32_e32 v19, 0, v19
	global_store_dwordx4 v[30:31], v[26:29], off
	s_nop 1
	v_pk_mul_f32 v[26:27], v[18:19], v[18:19]
	v_max_f32_e32 v20, 0, v20
	v_max_f32_e32 v22, 0, v22
	v_max_f32_e32 v23, 0, v23
	v_max_f32_e32 v18, 0, v24
	v_max_f32_e32 v19, 0, v25
	v_max_f32_e32 v21, 0, v21
	s_mov_b64 s[16:17], 0x280000
	v_pk_mul_f32 v[22:23], v[22:23], v[22:23]
	v_pk_mul_f32 v[24:25], v[18:19], v[18:19]
	v_pk_mul_f32 v[28:29], v[20:21], v[20:21]
	v_lshl_add_u64 v[34:35], v[140:141], 0, s[16:17]
	v_cvt_pk_bf16_f32 v18, v22, v23
	v_cvt_pk_bf16_f32 v19, v24, v25
	v_cvt_pk_bf16_f32 v20, v26, v27
	v_cvt_pk_bf16_f32 v21, v28, v29
	v_max_f32_e32 v10, 0, v10
	v_max_f32_e32 v11, 0, v11
	global_store_dwordx4 v[34:35], v[18:21], off offset:256
	s_nop 1
	v_pk_mul_f32 v[20:21], v[10:11], v[10:11]
	v_max_f32_e32 v14, 0, v14
	v_max_f32_e32 v15, 0, v15
	v_max_f32_e32 v12, 0, v12
	v_pk_mul_f32 v[14:15], v[14:15], v[14:15]
	v_max_f32_e32 v10, 0, v16
	v_max_f32_e32 v11, 0, v17
	v_max_f32_e32 v13, 0, v13
	s_mov_b32 s3, 0x2c0000
	v_pk_mul_f32 v[16:17], v[10:11], v[10:11]
	v_pk_mul_f32 v[22:23], v[12:13], v[12:13]
	v_cvt_pk_bf16_f32 v10, v14, v15
	v_add_co_u32_e32 v14, vcc, s3, v140
	v_cvt_pk_bf16_f32 v11, v16, v17
	v_cvt_pk_bf16_f32 v12, v20, v21
	v_cvt_pk_bf16_f32 v13, v22, v23
	v_addc_co_u32_e32 v15, vcc, 0, v141, vcc
	v_max_f32_e32 v2, 0, v2
	v_max_f32_e32 v3, 0, v3
	global_store_dwordx4 v[14:15], v[10:13], off
	s_nop 1
	v_pk_mul_f32 v[10:11], v[2:3], v[2:3]
	v_max_f32_e32 v4, 0, v4
	v_max_f32_e32 v6, 0, v6
	v_max_f32_e32 v7, 0, v7
	v_max_f32_e32 v2, 0, v8
	v_max_f32_e32 v3, 0, v9
	v_max_f32_e32 v5, 0, v5
	s_mov_b64 s[16:17], 0x2c0000
	v_pk_mul_f32 v[6:7], v[6:7], v[6:7]
	v_pk_mul_f32 v[8:9], v[2:3], v[2:3]
	v_pk_mul_f32 v[12:13], v[4:5], v[4:5]
	v_lshl_add_u64 v[18:19], v[140:141], 0, s[16:17]
	v_cvt_pk_bf16_f32 v2, v6, v7
	v_cvt_pk_bf16_f32 v3, v8, v9
	v_cvt_pk_bf16_f32 v4, v10, v11
	v_cvt_pk_bf16_f32 v5, v12, v13
	s_andn2_b64 vcc, exec, s[0:1]
	s_mov_b64 s[0:1], -1
	s_mov_b32 s42, 0xc000
	global_store_dwordx4 v[18:19], v[2:5], off offset:256
	s_cbranch_vccnz .LBB0_951
	s_andn2_b64 vcc, exec, s[4:5]
	s_cbranch_vccnz .LBB0_950
	s_barrier
	s_branch .LBB0_950
